# INPROJ0 conversion tail: tile loads as SGPR base + 32-bit lane offset, L2 warm-up two items ahead; PREP0: second-round w_in items moved from the modgemv virtual blocks to the converter-only blocks
# speedup vs baseline: 1.0028x; 1.0028x over previous
.LBB0_23:
	s_movk_i32 s99, 0x80
	s_cmpk_gt_i32 s3, 0x17f
	s_cselect_b32 s98, s99, 0x400
	s_add_i32 s27, s27, s98
	s_cmpk_lt_i32 s27, 0x400
	s_cbranch_scc0 .LBB0_75

.LBB0_327:
	s_add_i32 s73, s57, 0x3a8
	s_cmpk_gt_u32 s73, 0x27f
	s_mov_b64 s[4:5], -1
	s_cbranch_scc0 .LBB0_382
	s_cmpk_gt_u32 s73, 0x297
	s_cbranch_scc0 .LBB0_377
	s_cmpk_gt_u32 s73, 0x2a7
	s_cbranch_scc0 .LBB0_372
	s_cmpk_gt_u32 s73, 0x3a7
	s_cbranch_scc0 .LBB0_336
	s_cmpk_gt_u32 s73, 0x7a7
	s_cbranch_scc0 .LBB0_333
	s_add_i32 s0, s56, 0xffffe620
	v_mov_b32_e32 v21, v164
	s_and_b32 s1, s0, 0x7fffffc0
	s_add_i32 s0, s55, 0xfffe6200
	s_and_b32 s0, s0, 0x3c0
	v_and_b32_e32 v24, 63, v21
	v_bfe_u32 v25, v21, 6, 2
	s_lshl_b32 s98, s1, 12
	s_lshl_b32 s99, s0, 2
	s_add_i32 s98, s98, s99
	s_add_u32 s100, s30, s98
	s_addc_u32 s101, s31, 0
	v_lshlrev_b32_e32 v222, 12, v25
	v_lshl_add_u32 v222, v24, 2, v222
	s_mov_b32 s98, 0x4000
	global_load_dword v26, v222, s[100:101]
	s_add_u32 s100, s100, s98
	s_addc_u32 s101, s101, 0
	global_load_dword v27, v222, s[100:101]
	s_add_u32 s100, s100, s98
	s_addc_u32 s101, s101, 0
	global_load_dword v28, v222, s[100:101]
	s_add_u32 s100, s100, s98
	s_addc_u32 s101, s101, 0
	global_load_dword v29, v222, s[100:101]
	s_add_u32 s100, s100, s98
	s_addc_u32 s101, s101, 0
	global_load_dword v30, v222, s[100:101]
	s_add_u32 s100, s100, s98
	s_addc_u32 s101, s101, 0
	global_load_dword v31, v222, s[100:101]
	s_add_u32 s100, s100, s98
	s_addc_u32 s101, s101, 0
	global_load_dword v32, v222, s[100:101]
	s_add_u32 s100, s100, s98
	s_addc_u32 s101, s101, 0
	global_load_dword v22, v222, s[100:101]
	s_add_u32 s100, s100, s98
	s_addc_u32 s101, s101, 0
	global_load_dword v2, v222, s[100:101]
	s_add_u32 s100, s100, s98
	s_addc_u32 s101, s101, 0
	global_load_dword v3, v222, s[100:101]
	s_add_u32 s100, s100, s98
	s_addc_u32 s101, s101, 0
	global_load_dword v4, v222, s[100:101]
	s_add_u32 s100, s100, s98
	s_addc_u32 s101, s101, 0
	global_load_dword v5, v222, s[100:101]
	s_add_u32 s100, s100, s98
	s_addc_u32 s101, s101, 0
	global_load_dword v6, v222, s[100:101]
	s_add_u32 s100, s100, s98
	s_addc_u32 s101, s101, 0
	global_load_dword v7, v222, s[100:101]
	s_add_u32 s100, s100, s98
	s_addc_u32 s101, s101, 0
	global_load_dword v8, v222, s[100:101]
	s_add_u32 s100, s100, s98
	s_addc_u32 s101, s101, 0
	global_load_dword v0, v222, s[100:101]
	s_add_i32 s98, s73, 0x160
	s_cmpk_lt_i32 s98, 0xba8
	s_cselect_b32 s98, s98, s73
	s_cmpk_gt_u32 s98, 0x7a7
	s_cbranch_scc1 .LpfA_ff2
	s_add_i32 s98, s98, 0xfffffc58
	s_lshr_b32 s99, s98, 6
	s_and_b32 s98, s98, 63
	s_lshl_b32 s99, s99, 20
	s_lshl_b32 s98, s98, 8
	s_add_i32 s98, s98, s99
	s_add_u32 s100, s28, s98
	s_addc_u32 s101, s29, 0
	s_mov_b32 s99, 14
	s_branch .LpfA_go

.LBB0_333:
	s_andn2_b64 vcc, exec, s[4:5]
	s_cbranch_vccnz .LBB0_335
	v_mov_b32_e32 v21, v164
	s_add_i32 s0, s55, 0xffff6200
	s_and_b32 s0, s0, 0xfc0
	v_and_b32_e32 v24, 63, v21
	s_and_b32 s36, s57, 0xffffffc0
	v_bfe_u32 v25, v21, 6, 2
	s_lshl_b32 s98, s36, 14
	s_lshl_b32 s99, s0, 2
	s_add_i32 s98, s98, s99
	s_add_u32 s100, s28, s98
	s_addc_u32 s101, s29, 0
	v_lshlrev_b32_e32 v222, 14, v25
	v_lshl_add_u32 v222, v24, 2, v222
	s_mov_b32 s98, 0x10000
	global_load_dword v26, v222, s[100:101]
	s_add_u32 s100, s100, s98
	s_addc_u32 s101, s101, 0
	global_load_dword v27, v222, s[100:101]
	s_add_u32 s100, s100, s98
	s_addc_u32 s101, s101, 0
	global_load_dword v28, v222, s[100:101]
	s_add_u32 s100, s100, s98
	s_addc_u32 s101, s101, 0
	global_load_dword v29, v222, s[100:101]
	s_add_u32 s100, s100, s98
	s_addc_u32 s101, s101, 0
	global_load_dword v30, v222, s[100:101]
	s_add_u32 s100, s100, s98
	s_addc_u32 s101, s101, 0
	global_load_dword v31, v222, s[100:101]
	s_add_u32 s100, s100, s98
	s_addc_u32 s101, s101, 0
	global_load_dword v32, v222, s[100:101]
	s_add_u32 s100, s100, s98
	s_addc_u32 s101, s101, 0
	global_load_dword v22, v222, s[100:101]
	s_add_u32 s100, s100, s98
	s_addc_u32 s101, s101, 0
	global_load_dword v2, v222, s[100:101]
	s_add_u32 s100, s100, s98
	s_addc_u32 s101, s101, 0
	global_load_dword v3, v222, s[100:101]
	s_add_u32 s100, s100, s98
	s_addc_u32 s101, s101, 0
	global_load_dword v4, v222, s[100:101]
	s_add_u32 s100, s100, s98
	s_addc_u32 s101, s101, 0
	global_load_dword v5, v222, s[100:101]
	s_add_u32 s100, s100, s98
	s_addc_u32 s101, s101, 0
	global_load_dword v6, v222, s[100:101]
	s_add_u32 s100, s100, s98
	s_addc_u32 s101, s101, 0
	global_load_dword v7, v222, s[100:101]
	s_add_u32 s100, s100, s98
	s_addc_u32 s101, s101, 0
	global_load_dword v8, v222, s[100:101]
	s_add_u32 s100, s100, s98
	s_addc_u32 s101, s101, 0
	global_load_dword v0, v222, s[100:101]
	s_add_i32 s98, s73, 0x160
	s_cmpk_lt_i32 s98, 0xba8
	s_cselect_b32 s98, s98, s73
	s_cmpk_gt_u32 s98, 0x7a7
	s_cbranch_scc1 .LpfB_ff2
	s_add_i32 s98, s98, 0xfffffc58
	s_lshr_b32 s99, s98, 6
	s_and_b32 s98, s98, 63
	s_lshl_b32 s99, s99, 20
	s_lshl_b32 s98, s98, 8
	s_add_i32 s98, s98, s99
	s_add_u32 s100, s28, s98
	s_addc_u32 s101, s29, 0
	s_mov_b32 s99, 14
	s_branch .LpfB_go
